# attention: running reference enters the QK^T MFMA as SrcC so the 32 v_sub per step go away; fixed the VALU-write to MFMA-operand 2-state hazard the removal exposed (s_nop); outputs identical to baseli
# speedup vs baseline: 1.0193x; 1.0018x over previous
; #define MFMA(a, b, c) __builtin_amdgcn_mfma_f32_32x32x16_bf16((a), (b), (c), 0, 0, 0)
; DI float fexp2(float x) { return __builtin_amdgcn_exp2f(x); }
; DI void phase_attn(const Params& p, int hf, bool skipctx, char* smem, int& rot) {
;     ...
;       {
;         bf16x8 kf[2][6];
; #pragma unroll
;         for (int kb = 0; kb < 2; ++kb)
; #pragma unroll
;           for (int ks = 0; ks < 6; ++ks) kf[kb][ks] = *(const bf16x8*)(sk + (kb * 32 + r) * KROW + (ks * 16 + h * 8) * 2);
;         __builtin_amdgcn_sched_barrier(0);
; #pragma unroll
;         for (int ks = 0; ks < 6; ++ks)
; #pragma unroll
;           for (int kb = 0; kb < 2; ++kb) st[kb] = MFMA(kf[kb][ks], qf[ks], st[kb]);
;         __builtin_amdgcn_sched_barrier(0);
;       }
;       bf16x8 vf[2][2][2];
; #pragma unroll
;       for (int kb = 0; kb < 2; ++kb)
; #pragma unroll
;         for (int s2 = 0; s2 < 2; ++s2)
; #pragma unroll
;           for (int dvb = 0; dvb < 2; ++dvb) {
;             const char* vp = sv + (dvb * 32 + r) * VROW + (kb * 32 + 16 * s2 + 4 * h) * 2;
;             const s16x4 lo = *(const s16x4*)vp, hi = *(const s16x4*)(vp + 16);
;             vf[kb][s2][dvb] = __builtin_shufflevector(lo, hi, 0, 1, 2, 3, 4, 5, 6, 7);
;           }
;       float mx = st[0][0];
; #pragma unroll
;       for (int i = 0; i < 16; ++i) { mx = fmaxf(mx, st[0][i]); mx = fmaxf(mx, st[1][i]); }
;       if (__any(mx > m_run + 8.f)) {
;         mx = fmaxf(mx, __shfl_xor(mx, 32));
;         const float m_new = fmaxf(m_run, mx);
;         const float alpha = fexp2(m_run - m_new);
;         m_run = m_new;
;         l_run *= alpha;
; #pragma unroll
;         for (int i = 0; i < 16; ++i) { o[0][i] *= alpha; o[1][i] *= alpha; }
;       }
;       float ps = 0.f;
; #pragma unroll
;       for (int kb = 0; kb < 2; ++kb)
; #pragma unroll
;         for (int i = 0; i < 16; ++i) { const float e = fexp2(st[kb][i] - m_run); st[kb][i] = e; ps += e; }
;       l_run += ps;
; #pragma unroll
;       for (int kb = 0; kb < 2; ++kb)
; #pragma unroll
;         for (int s2 = 0; s2 < 2; ++s2) {
;           const bf16x8 pb = pack8(st[kb][8 * s2 + 0], st[kb][8 * s2 + 1], st[kb][8 * s2 + 2], st[kb][8 * s2 + 3], st[kb][8 * s2 + 4], st[kb][8 * s2 + 5], st[kb][8 * s2 + 6], st[kb][8 * s2 + 7]);
; #pragma unroll
;           for (int dvb = 0; dvb < 2; ++dvb) o[dvb] = MFMA(vf[kb][s2][dvb], pb, o[dvb]);
;         }
.LBB0_799:
	v_exp_f32_e32 v48, v48
	v_exp_f32_e32 v49, v49
	v_exp_f32_e32 v50, v50
	v_exp_f32_e32 v51, v51
	v_add_f32_e32 v195, 0, v48
	v_exp_f32_e32 v52, v52
	v_add_f32_e32 v195, v49, v195
	v_exp_f32_e32 v53, v53
	v_add_f32_e32 v195, v50, v195
	v_exp_f32_e32 v54, v54
	v_add_f32_e32 v195, v51, v195
	v_exp_f32_e32 v55, v55
	v_add_f32_e32 v195, v52, v195
	v_exp_f32_e32 v56, v56
	v_add_f32_e32 v195, v53, v195
	v_exp_f32_e32 v57, v57
	v_add_f32_e32 v195, v54, v195
	v_exp_f32_e32 v58, v58
	v_add_f32_e32 v195, v55, v195
	v_exp_f32_e32 v59, v59
	v_add_f32_e32 v195, v56, v195
	v_exp_f32_e32 v60, v60
	v_add_f32_e32 v195, v57, v195
	v_exp_f32_e32 v61, v61
	v_add_f32_e32 v195, v58, v195
	v_exp_f32_e32 v62, v62
	v_add_f32_e32 v195, v59, v195
	v_exp_f32_e32 v63, v63
	v_add_f32_e32 v195, v60, v195
	v_exp_f32_e32 v200, v32
	v_add_f32_e32 v195, v61, v195
	v_exp_f32_e32 v201, v33
	v_add_f32_e32 v32, v62, v195
	v_exp_f32_e32 v195, v34
	v_add_f32_e32 v32, v63, v32
	v_exp_f32_e32 v202, v35
	v_add_f32_e32 v32, v200, v32
	v_exp_f32_e32 v36, v36
	v_add_f32_e32 v32, v201, v32
	v_exp_f32_e32 v37, v37
	v_add_f32_e32 v32, v195, v32
	v_add_f32_e32 v32, v202, v32
	v_add_f32_e32 v32, v36, v32
	v_add_f32_e32 v203, v37, v32
	v_cvt_pk_bf16_f32 v32, v48, v49
	v_cvt_pk_bf16_f32 v33, v50, v51
	v_cvt_pk_bf16_f32 v34, v52, v53
	v_cvt_pk_bf16_f32 v35, v54, v55
	v_exp_f32_e32 v38, v38
	s_waitcnt lgkmcnt(7)
	v_mfma_f32_32x32x16_bf16 v[16:31], v[156:159], v[32:35], v[16:31]
	v_exp_f32_e32 v39, v39
	v_exp_f32_e32 v40, v40
	v_add_f32_e32 v48, v38, v203
	v_exp_f32_e32 v42, v42
	s_waitcnt lgkmcnt(5)
	v_mfma_f32_32x32x16_bf16 v[0:15], v[152:155], v[32:35], v[0:15]
	v_exp_f32_e32 v41, v41
	v_cvt_pk_bf16_f32 v32, v56, v57
	v_cvt_pk_bf16_f32 v33, v58, v59
	v_cvt_pk_bf16_f32 v34, v60, v61
	v_cvt_pk_bf16_f32 v35, v62, v63
	v_add_f32_e32 v48, v39, v48
	s_nop 0
	v_mfma_f32_32x32x16_bf16 v[16:31], v[148:151], v[32:35], v[16:31]
	v_exp_f32_e32 v43, v43
	v_add_f32_e32 v48, v40, v48
	v_exp_f32_e32 v44, v44
	v_add_f32_e32 v48, v41, v48
	s_waitcnt lgkmcnt(4)
	v_mfma_f32_32x32x16_bf16 v[0:15], v[144:147], v[32:35], v[0:15]
	v_add_f32_e32 v32, v42, v48
	v_add_f32_e32 v32, v43, v32
	v_add_f32_e32 v48, v44, v32
	v_cvt_pk_bf16_f32 v32, v200, v201
	v_cvt_pk_bf16_f32 v33, v195, v202
	v_cvt_pk_bf16_f32 v34, v36, v37
	v_cvt_pk_bf16_f32 v35, v38, v39
	v_exp_f32_e32 v36, v45
	s_waitcnt lgkmcnt(3)
	v_mfma_f32_32x32x16_bf16 v[16:31], v[140:143], v[32:35], v[16:31]
	v_exp_f32_e32 v37, v46
	v_exp_f32_e32 v38, v47
	v_add_f32_e32 v39, v36, v48
	s_waitcnt lgkmcnt(2)
	v_mfma_f32_32x32x16_bf16 v[0:15], v[136:139], v[32:35], v[0:15]
	v_add_f32_e32 v32, v37, v39
	v_add_f32_e32 v32, v38, v32
	v_add_f32_e32 v213, v213, v32
	v_cvt_pk_bf16_f32 v32, v40, v41
	v_cvt_pk_bf16_f32 v33, v42, v43
	v_cvt_pk_bf16_f32 v34, v44, v36
	v_cvt_pk_bf16_f32 v35, v37, v38
	s_waitcnt lgkmcnt(1)
	s_nop 0
	v_mfma_f32_32x32x16_bf16 v[16:31], v[132:135], v[32:35], v[16:31]
	ds_read_b128 v[36:39], v210 offset:13312
	ds_read_b128 v[132:135], v210 offset:13344
	ds_read_b128 v[136:139], v210 offset:13376
	ds_read_b128 v[140:143], v210 offset:13408
	ds_read_b128 v[144:147], v210 offset:13440
	ds_read_b128 v[148:151], v210 offset:13472
	ds_read_b128 v[40:43], v210 offset:19968
	ds_read_b128 v[152:155], v210 offset:20000
	ds_read_b128 v[156:159], v210 offset:20032
	ds_read_b128 v[234:237], v210 offset:20064
	ds_read_b128 v[238:241], v210 offset:20096
	ds_read_b128 v[242:245], v210 offset:20128
	s_waitcnt lgkmcnt(12)
	v_mfma_f32_32x32x16_bf16 v[0:15], v[128:131], v[32:35], v[0:15]
	s_waitcnt lgkmcnt(11)
	v_mfma_f32_32x32x16_bf16 v[48:63], v[36:39], v[64:67], v[176:191]
	s_waitcnt lgkmcnt(5)
	v_mfma_f32_32x32x16_bf16 v[32:47], v[40:43], v[64:67], v[176:191]
	v_mfma_f32_32x32x16_bf16 v[48:63], v[132:135], v[68:71], v[48:63]
	s_waitcnt lgkmcnt(4)
	v_mfma_f32_32x32x16_bf16 v[32:47], v[152:155], v[68:71], v[32:47]
	v_mfma_f32_32x32x16_bf16 v[48:63], v[136:139], v[72:75], v[48:63]
	s_waitcnt lgkmcnt(3)
	v_mfma_f32_32x32x16_bf16 v[32:47], v[156:159], v[72:75], v[32:47]
	v_mfma_f32_32x32x16_bf16 v[48:63], v[140:143], v[88:91], v[48:63]
	s_waitcnt lgkmcnt(2)
	v_mfma_f32_32x32x16_bf16 v[32:47], v[234:237], v[88:91], v[32:47]
	v_mfma_f32_32x32x16_bf16 v[48:63], v[144:147], v[96:99], v[48:63]
	s_waitcnt lgkmcnt(1)
	v_mfma_f32_32x32x16_bf16 v[32:47], v[238:241], v[96:99], v[32:47]
	v_mfma_f32_32x32x16_bf16 v[48:63], v[148:151], v[100:103], v[48:63]
	s_waitcnt lgkmcnt(0)
	v_mfma_f32_32x32x16_bf16 v[32:47], v[242:245], v[100:103], v[32:47]
	s_nop 3
	ds_read_b128 v[156:159], v211 offset:128
	ds_read_b128 v[148:151], v211 offset:160
	ds_read_b128 v[152:155], v211 offset:8832
	ds_read_b128 v[144:147], v211 offset:8864
	ds_read_b128 v[140:143], v211 offset:192
	ds_read_b128 v[136:139], v211 offset:8896
	ds_read_b128 v[128:131], v211 offset:224
	ds_read_b128 v[132:135], v211 offset:8928
	v_max_f32_e32 v195, v32, v32
	v_max_f32_e32 v200, v48, v48
	v_max_f32_e32 v195, v200, v195
	v_max3_f32 v195, v195, v49, v33
	v_max3_f32 v195, v195, v50, v34
	v_max3_f32 v195, v195, v51, v35
	v_max3_f32 v195, v195, v52, v36
	v_max3_f32 v195, v195, v53, v37
	v_max3_f32 v195, v195, v54, v38
	v_max3_f32 v195, v195, v55, v39
	v_max3_f32 v195, v195, v56, v40
	v_max3_f32 v195, v195, v57, v41
	v_max3_f32 v195, v195, v58, v42
	v_max3_f32 v195, v195, v59, v43
	v_max3_f32 v195, v195, v60, v44
	v_max3_f32 v195, v195, v61, v45
	v_max3_f32 v195, v195, v62, v46
	v_max3_f32 v214, v195, v63, v47
	v_cmp_gt_f32_e32 vcc, v214, v220
	s_cbranch_vccz .LBB0_801
; #define MFMA(a, b, c) __builtin_amdgcn_mfma_f32_32x32x16_bf16((a), (b), (c), 0, 0, 0)
; DI float fexp2(float x) { return __builtin_amdgcn_exp2f(x); }
; DI void phase_attn(const Params& p, int hf, bool skipctx, char* smem, int& rot) {
;     ...
;       if (__any(mx > m_run + 8.f)) {
;         mx = fmaxf(mx, __shfl_xor(mx, 32));
;         const float m_new = fmaxf(m_run, mx);
;         const float alpha = fexp2(m_run - m_new);
;         m_run = m_new;
;         l_run *= alpha;
; #pragma unroll
;         for (int i = 0; i < 16; ++i) { o[0][i] *= alpha; o[1][i] *= alpha; }
;       }
;       float ps = 0.f;
; #pragma unroll
;       for (int kb = 0; kb < 2; ++kb)
; #pragma unroll
;         for (int i = 0; i < 16; ++i) { const float e = fexp2(st[kb][i] - m_run); st[kb][i] = e; ps += e; }
;       l_run += ps;
; #pragma unroll
;       for (int kb = 0; kb < 2; ++kb)
; #pragma unroll
;         for (int s2 = 0; s2 < 2; ++s2) {
;           const bf16x8 pb = pack8(st[kb][8 * s2 + 0], st[kb][8 * s2 + 1], st[kb][8 * s2 + 2], st[kb][8 * s2 + 3], st[kb][8 * s2 + 4], st[kb][8 * s2 + 5], st[kb][8 * s2 + 6], st[kb][8 * s2 + 7]);
; #pragma unroll
;           for (int dvb = 0; dvb < 2; ++dvb) o[dvb] = MFMA(vf[kb][s2][dvb], pb, o[dvb]);
;         }
;     };
;     __syncthreads();
;     ATT_LOAD(ak0, ak1, ak2, av0, av1, 0);
;     ATT_LOAD(bk0, bk1, bk2, bv0, bv1, 1);
;     ATT_WRITE(ak0, ak1, ak2, av0, av1, 0);
;     __syncthreads();
;     for (int kt = 0; kt < nkt; kt += 2) {
;       if (kt + 2 < nkt) ATT_LOAD(ak0, ak1, ak2, av0, av1, kt + 2);
;       compute(0, 0); compute(0, 1);
;       ATT_WRITE(bk0, bk1, bk2, bv0, bv1, 1);
;       __syncthreads();
;       if (kt + 3 < nkt) ATT_LOAD(bk0, bk1, bk2, bv0, bv1, kt + 3);
;       compute(1, 0); compute(1, 1);
;       if (kt + 2 < nkt) ATT_WRITE(ak0, ak1, ak2, av0, av1, 0);
	v_sub_f32_e32 v214, v214, v176
	v_cmp_lt_i32_e32 vcc, v224, v207
	s_nop 1
	v_cndmask_b32_e32 v195, v205, v224, vcc
	v_lshlrev_b32_e32 v195, 2, v195
	ds_bpermute_b32 v195, v195, v214
	s_waitcnt lgkmcnt(0)
	v_max3_f32 v195, v212, v214, v195
	v_sub_f32_e32 v200, v212, v195
	v_exp_f32_e32 v200, v200
	v_mov_b32_e32 v212, v195
	v_mul_f32_e32 v213, v213, v200
	v_pk_mul_f32 v[30:31], v[30:31], v[200:201] op_sel_hi:[1,0]
	v_pk_mul_f32 v[28:29], v[28:29], v[200:201] op_sel_hi:[1,0]
	v_pk_mul_f32 v[26:27], v[26:27], v[200:201] op_sel_hi:[1,0]
	v_pk_mul_f32 v[24:25], v[24:25], v[200:201] op_sel_hi:[1,0]
	v_pk_mul_f32 v[22:23], v[22:23], v[200:201] op_sel_hi:[1,0]
	v_pk_mul_f32 v[20:21], v[20:21], v[200:201] op_sel_hi:[1,0]
	v_pk_mul_f32 v[18:19], v[18:19], v[200:201] op_sel_hi:[1,0]
	v_pk_mul_f32 v[16:17], v[16:17], v[200:201] op_sel_hi:[1,0]
	v_pk_mul_f32 v[14:15], v[14:15], v[200:201] op_sel_hi:[1,0]
	v_pk_mul_f32 v[12:13], v[12:13], v[200:201] op_sel_hi:[1,0]
	v_pk_mul_f32 v[10:11], v[10:11], v[200:201] op_sel_hi:[1,0]
	v_pk_mul_f32 v[8:9], v[8:9], v[200:201] op_sel_hi:[1,0]
	v_pk_mul_f32 v[6:7], v[6:7], v[200:201] op_sel_hi:[1,0]
	v_pk_mul_f32 v[4:5], v[4:5], v[200:201] op_sel_hi:[1,0]
	v_pk_mul_f32 v[2:3], v[2:3], v[200:201] op_sel_hi:[1,0]
	v_pk_mul_f32 v[0:1], v[0:1], v[200:201] op_sel_hi:[1,0]
	v_add_f32_e32 v202, v195, v176
	v_sub_f32_e32 v32, v32, v202
	v_sub_f32_e32 v33, v33, v202
	v_sub_f32_e32 v34, v34, v202
	v_sub_f32_e32 v35, v35, v202
	v_sub_f32_e32 v36, v36, v202
	v_sub_f32_e32 v37, v37, v202
	v_sub_f32_e32 v38, v38, v202
	v_sub_f32_e32 v39, v39, v202
	v_sub_f32_e32 v40, v40, v202
	v_sub_f32_e32 v41, v41, v202
	v_sub_f32_e32 v42, v42, v202
	v_sub_f32_e32 v43, v43, v202
	v_sub_f32_e32 v44, v44, v202
	v_sub_f32_e32 v45, v45, v202
	v_sub_f32_e32 v46, v46, v202
	v_sub_f32_e32 v47, v47, v202
	v_sub_f32_e32 v48, v48, v202
	v_sub_f32_e32 v49, v49, v202
	v_sub_f32_e32 v50, v50, v202
	v_sub_f32_e32 v51, v51, v202
	v_sub_f32_e32 v52, v52, v202
	v_sub_f32_e32 v53, v53, v202
	v_sub_f32_e32 v54, v54, v202
	v_sub_f32_e32 v55, v55, v202
	v_sub_f32_e32 v56, v56, v202
	v_sub_f32_e32 v57, v57, v202
	v_sub_f32_e32 v58, v58, v202
	v_sub_f32_e32 v59, v59, v202
	v_sub_f32_e32 v60, v60, v202
	v_sub_f32_e32 v61, v61, v202
	v_sub_f32_e32 v62, v62, v202
	v_sub_f32_e32 v63, v63, v202
	v_sub_f32_e32 v176, 0, v195
	v_sub_f32_e32 v177, 0, v195
	v_sub_f32_e32 v178, 0, v195
	v_sub_f32_e32 v179, 0, v195
	v_sub_f32_e32 v180, 0, v195
	v_sub_f32_e32 v181, 0, v195
	v_sub_f32_e32 v182, 0, v195
	v_sub_f32_e32 v183, 0, v195
	v_sub_f32_e32 v184, 0, v195
	v_sub_f32_e32 v185, 0, v195
	v_sub_f32_e32 v186, 0, v195
	v_sub_f32_e32 v187, 0, v195
	v_sub_f32_e32 v188, 0, v195
	v_sub_f32_e32 v189, 0, v195
	v_sub_f32_e32 v190, 0, v195
	v_sub_f32_e32 v191, 0, v195
	v_mov_b32_e32 v220, 0x41000000
.LBB0_801:
	v_exp_f32_e32 v48, v48
	v_exp_f32_e32 v49, v49
	v_exp_f32_e32 v50, v50
	v_exp_f32_e32 v51, v51
	v_exp_f32_e32 v52, v52
	v_exp_f32_e32 v53, v53
	v_exp_f32_e32 v54, v54
	v_exp_f32_e32 v55, v55
	v_cvt_pk_bf16_f32 v214, v48, v49
	v_cvt_pk_bf16_f32 v215, v50, v51
	v_cvt_pk_bf16_f32 v216, v52, v53
	v_cvt_pk_bf16_f32 v217, v54, v55
	s_waitcnt lgkmcnt(7)
	s_nop 0
	v_mfma_f32_32x32x16_bf16 v[16:31], v[156:159], v[214:217], v[16:31]
	v_exp_f32_e32 v56, v56
	s_waitcnt lgkmcnt(5)
	v_mfma_f32_32x32x16_bf16 v[0:15], v[152:155], v[214:217], v[0:15]
	v_exp_f32_e32 v57, v57
	v_exp_f32_e32 v58, v58
	v_exp_f32_e32 v59, v59
	v_exp_f32_e32 v60, v60
	v_exp_f32_e32 v61, v61
	v_exp_f32_e32 v62, v62
	v_exp_f32_e32 v63, v63
	v_cvt_pk_bf16_f32 v152, v56, v57
	v_cvt_pk_bf16_f32 v153, v58, v59
	v_cvt_pk_bf16_f32 v154, v60, v61
	v_cvt_pk_bf16_f32 v155, v62, v63
	s_nop 1
	v_mfma_f32_32x32x16_bf16 v[16:31], v[148:151], v[152:155], v[16:31]
	v_exp_f32_e32 v32, v32
	s_waitcnt lgkmcnt(4)
	v_mfma_f32_32x32x16_bf16 v[0:15], v[144:147], v[152:155], v[0:15]
	v_exp_f32_e32 v33, v33
	v_exp_f32_e32 v34, v34
	v_exp_f32_e32 v35, v35
	v_exp_f32_e32 v36, v36
	v_exp_f32_e32 v37, v37
	v_exp_f32_e32 v38, v38
	v_exp_f32_e32 v39, v39
	v_cvt_pk_bf16_f32 v144, v32, v33
	v_cvt_pk_bf16_f32 v145, v34, v35
	v_cvt_pk_bf16_f32 v146, v36, v37
	v_cvt_pk_bf16_f32 v147, v38, v39
	s_waitcnt lgkmcnt(3)
	s_nop 0
	v_mfma_f32_32x32x16_bf16 v[16:31], v[140:143], v[144:147], v[16:31]
	v_exp_f32_e32 v40, v40
	s_waitcnt lgkmcnt(2)
	v_mfma_f32_32x32x16_bf16 v[0:15], v[136:139], v[144:147], v[0:15]
	v_exp_f32_e32 v41, v41
	v_exp_f32_e32 v42, v42
	v_exp_f32_e32 v43, v43
	v_exp_f32_e32 v44, v44
	v_exp_f32_e32 v45, v45
	v_exp_f32_e32 v46, v46
	v_exp_f32_e32 v47, v47
	v_cvt_pk_bf16_f32 v136, v40, v41
	v_cvt_pk_bf16_f32 v137, v42, v43
	v_cvt_pk_bf16_f32 v138, v44, v45
	v_cvt_pk_bf16_f32 v139, v46, v47
	s_add_i32 s4, s4, 3
	s_cmp_ge_u32 s4, s13
	s_waitcnt lgkmcnt(1)
	v_mfma_f32_32x32x16_bf16 v[16:31], v[128:131], v[136:139], v[16:31]
	s_waitcnt vmcnt(1)
	ds_write_b128 v194, v[112:115] offset:44032
	ds_write_b128 v204, v[108:111] offset:44032
	ds_write_b128 v206, v[116:119] offset:44032
	ds_write_b64 v208, v[120:121] offset:44032
	ds_write_b64 v208, v[122:123] offset:44048
	s_waitcnt vmcnt(0)
	ds_write_b64 v208, v[124:125] offset:52736
	ds_write_b64 v208, v[126:127] offset:52752
	s_waitcnt lgkmcnt(0)
	s_barrier
	v_mfma_f32_32x32x16_bf16 v[0:15], v[132:135], v[136:139], v[0:15]
	s_cbranch_scc1 .LBB0_803
	v_lshl_add_u64 v[108:109], s[94:95], 0, v[174:175]
	v_add_co_u32_e32 v108, vcc, 0x18b2e000, v108
	v_lshl_add_u64 v[110:111], s[94:95], 0, v[172:173]
	s_nop 0
	v_addc_co_u32_e32 v109, vcc, 0, v109, vcc
	v_add_co_u32_e32 v110, vcc, 0x18b2e000, v110
	v_lshl_add_u64 v[116:117], s[94:95], 0, v[170:171]
	s_nop 0
	v_addc_co_u32_e32 v111, vcc, 0, v111, vcc
	v_add_co_u32_e32 v116, vcc, 0x18b2e000, v116
	v_lshl_add_u64 v[120:121], s[94:95], 0, v[166:167]
	s_nop 0
	v_addc_co_u32_e32 v117, vcc, 0, v117, vcc
	v_lshl_add_u64 v[124:125], s[94:95], 0, v[168:169]
	global_load_dwordx4 v[112:115], v[108:109], off
	s_nop 0
	global_load_dwordx4 v[108:111], v[110:111], off
	s_nop 0
	global_load_dwordx4 v[116:119], v[116:117], off
	s_nop 0
	global_load_dwordx4 v[120:123], v[120:121], off
	s_nop 0
	global_load_dwordx4 v[124:127], v[124:125], off

; #define MFMA(a, b, c) __builtin_amdgcn_mfma_f32_32x32x16_bf16((a), (b), (c), 0, 0, 0)
; DI float fexp2(float x) { return __builtin_amdgcn_exp2f(x); }
; DI void phase_attn(const Params& p, int hf, bool skipctx, char* smem, int& rot) {
;     ...
;       float ps = 0.f;
; #pragma unroll
;       for (int kb = 0; kb < 2; ++kb)
; #pragma unroll
;         for (int i = 0; i < 16; ++i) { const float e = fexp2(st[kb][i] - m_run); st[kb][i] = e; ps += e; }
;       l_run += ps;
; #pragma unroll
;       for (int kb = 0; kb < 2; ++kb)
; #pragma unroll
;         for (int s2 = 0; s2 < 2; ++s2) {
;           const bf16x8 pb = pack8(st[kb][8 * s2 + 0], st[kb][8 * s2 + 1], st[kb][8 * s2 + 2], st[kb][8 * s2 + 3], st[kb][8 * s2 + 4], st[kb][8 * s2 + 5], st[kb][8 * s2 + 6], st[kb][8 * s2 + 7]);
; #pragma unroll
;           for (int dvb = 0; dvb < 2; ++dvb) o[dvb] = MFMA(vf[kb][s2][dvb], pb, o[dvb]);
;         }
;     ...
;       if (kt + 2 < nkt) ATT_WRITE(ak0, ak1, ak2, av0, av1, 0);
.LBB0_807:
	v_exp_f32_e32 v48, v48
	v_exp_f32_e32 v49, v49
	v_exp_f32_e32 v50, v50
	v_exp_f32_e32 v51, v51
	v_exp_f32_e32 v52, v52
	v_exp_f32_e32 v53, v53
	v_exp_f32_e32 v54, v54
	v_exp_f32_e32 v55, v55
	v_cvt_pk_bf16_f32 v214, v48, v49
	v_cvt_pk_bf16_f32 v215, v50, v51
	v_cvt_pk_bf16_f32 v216, v52, v53
	v_cvt_pk_bf16_f32 v217, v54, v55
	s_waitcnt lgkmcnt(6)
	s_nop 0
	v_mfma_f32_32x32x16_bf16 v[16:31], v[156:159], v[214:217], v[16:31]
	v_exp_f32_e32 v56, v56
	v_mfma_f32_32x32x16_bf16 v[0:15], v[152:155], v[214:217], v[0:15]
	v_exp_f32_e32 v57, v57
	v_exp_f32_e32 v58, v58
	v_exp_f32_e32 v59, v59
	v_exp_f32_e32 v60, v60
	v_exp_f32_e32 v61, v61
	v_exp_f32_e32 v62, v62
	v_exp_f32_e32 v63, v63
	v_cvt_pk_bf16_f32 v152, v56, v57
	v_cvt_pk_bf16_f32 v153, v58, v59
	v_cvt_pk_bf16_f32 v154, v60, v61
	v_cvt_pk_bf16_f32 v155, v62, v63
	s_waitcnt lgkmcnt(5)
	s_nop 0
	v_mfma_f32_32x32x16_bf16 v[16:31], v[148:151], v[152:155], v[16:31]
	v_exp_f32_e32 v32, v32
	s_waitcnt lgkmcnt(4)
	v_mfma_f32_32x32x16_bf16 v[0:15], v[144:147], v[152:155], v[0:15]
	v_exp_f32_e32 v33, v33
	v_exp_f32_e32 v34, v34
	v_exp_f32_e32 v35, v35
	v_exp_f32_e32 v36, v36
	v_exp_f32_e32 v37, v37
	v_exp_f32_e32 v38, v38
	v_exp_f32_e32 v39, v39
	v_cvt_pk_bf16_f32 v144, v32, v33
	v_cvt_pk_bf16_f32 v145, v34, v35
	v_cvt_pk_bf16_f32 v146, v36, v37
	v_cvt_pk_bf16_f32 v147, v38, v39
	s_waitcnt lgkmcnt(3)
	s_nop 0
	v_mfma_f32_32x32x16_bf16 v[16:31], v[140:143], v[144:147], v[16:31]
	v_exp_f32_e32 v40, v40
	s_waitcnt lgkmcnt(2)
	v_mfma_f32_32x32x16_bf16 v[0:15], v[136:139], v[144:147], v[0:15]
	v_exp_f32_e32 v41, v41
	v_exp_f32_e32 v42, v42
	v_exp_f32_e32 v43, v43
	v_exp_f32_e32 v44, v44
	v_exp_f32_e32 v45, v45
	v_exp_f32_e32 v46, v46
	v_exp_f32_e32 v47, v47
	v_cvt_pk_bf16_f32 v136, v40, v41
	v_cvt_pk_bf16_f32 v137, v42, v43
	v_cvt_pk_bf16_f32 v138, v44, v45
	v_cvt_pk_bf16_f32 v139, v46, v47
	s_andn2_b64 vcc, exec, s[36:37]
	s_waitcnt lgkmcnt(1)
	v_mfma_f32_32x32x16_bf16 v[16:31], v[132:135], v[136:139], v[16:31]
	s_waitcnt lgkmcnt(0)
	v_mfma_f32_32x32x16_bf16 v[0:15], v[128:131], v[136:139], v[0:15]
	s_cbranch_vccnz .LBB0_809
	ds_write_b128 v194, v[76:79]
	ds_write_b128 v204, v[80:83]
	ds_write_b128 v206, v[84:87]
	ds_write_b64 v208, v[92:93] offset:0
	ds_write_b64 v208, v[94:95] offset:16
	ds_write_b64 v208, v[104:105] offset:8704
	ds_write_b64 v208, v[106:107] offset:8720
